# attention QK sections: 34 (was 20) finishSM VALU units issued under the opening K-fragment LDS latency
# baseline (speedup 1.0000x reference)
; __device__ __forceinline__ void finishSM(f32x16& p0, f32x16& p1, float alpha, float& l_reg, bf16x8& pa0, bf16x8& pa1, bf16x8& pa2, bf16x8& pa3) {
;     for (int r = 0; r < 16; ++r) p1[r] = __builtin_amdgcn_exp2f(p1[r]);
;     float ps = 0; for (int r = 0; r < 16; ++r) ps += p0[r]; for (int r = 0; r < 16; ++r) ps += p1[r];
;     { auto rr = __builtin_amdgcn_permlane32_swap(__float_as_uint(ps), __float_as_uint(ps), false, false);
;       ps = __uint_as_float(rr[0]) + __uint_as_float(rr[1]); }
;     l_reg = l_reg * alpha + ps;
;     ...
;     PK4(p0, 0, pa0); PK4(p0, 8, pa1); PK4(p1, 0, pa2); PK4(p1, 8, pa3);
;     ...
; }
; template <int KB>
; __device__ __forceinline__ void qkt(f32x16& p0, f32x16& p1, const char* K_lds, int r32, int hi, const bf16x8* qr) {
;     p0 = f32x16{}; p1 = f32x16{};
;     const char* kb[4];
; #pragma unroll
;     for (int dd = 0; dd < 4; ++dd) kb[dd] = K_lds + KB * SHM_K + KSWZ(r32, (dd * 16 + hi * 8) * 2);
; #pragma unroll
;     for (int d0 = 0; d0 < 8; ++d0) { const char* a = kb[d0 & 3] + (d0 >> 2) * 128;
;         bf16x8 b0 = *reinterpret_cast<const bf16x8*>(a);
;         bf16x8 b1 = *reinterpret_cast<const bf16x8*>(a + 32 * 256);
;         p0 = __builtin_amdgcn_mfma_f32_32x32x16_bf16(b0, qr[d0], p0, 0, 0, 0);
;         p1 = __builtin_amdgcn_mfma_f32_32x32x16_bf16(b1, qr[d0], p1, 0, 0, 0); }
; }
.Lmy_hs1_nov:
	s_mov_b32 s100, 0
	v_add_f32_e32 v148, 0, v231
	v_add_f32_e32 v148, v233, v148
	v_add_f32_e32 v148, v229, v148
	v_add_f32_e32 v148, v232, v148
	v_add_f32_e32 v148, v228, v148
	v_add_f32_e32 v148, v230, v148
	v_add_f32_e32 v148, v226, v148
	v_add_f32_e32 v148, v227, v148
	v_add_f32_e32 v148, v223, v148
	v_add_f32_e32 v148, v225, v148
	v_add_f32_e32 v148, v209, v148
	v_add_f32_e32 v148, v224, v148
	v_add_f32_e32 v148, v206, v148
	v_add_f32_e32 v148, v208, v148
	v_add_f32_e32 v148, v205, v148
	v_add_f32_e32 v148, v207, v148
	v_exp_f32_e32 v140, v152
	v_exp_f32_e32 v141, v153
	v_exp_f32_e32 v142, v180
	v_exp_f32_e32 v143, v181
	v_exp_f32_e32 v144, v160
	v_exp_f32_e32 v145, v161
	v_exp_f32_e32 v146, v154
	v_exp_f32_e32 v147, v155
	v_exp_f32_e32 v178, v178
	v_exp_f32_e32 v179, v179
	v_exp_f32_e32 v162, v162
	v_exp_f32_e32 v163, v163
	v_add_f32_e32 v148, v178, v148
	v_add_f32_e32 v148, v179, v148
	v_add_f32_e32 v148, v162, v148
	v_exp_f32_e32 v158, v158
	v_exp_f32_e32 v159, v159
	v_exp_f32_e32 v156, v156
	s_waitcnt lgkmcnt(3)
	v_mfma_f32_32x32x16_bf16 v[82:97], v[66:69], v[132:135], 0
	v_exp_f32_e32 v157, v157
	v_add_f32_e32 v148, v163, v148
	v_add_f32_e32 v148, v158, v148
	s_waitcnt lgkmcnt(2)
	v_mfma_f32_32x32x16_bf16 v[66:81], v[70:73], v[132:135], 0
	v_add_f32_e32 v148, v159, v148
	v_add_f32_e32 v148, v156, v148
	v_add_f32_e32 v148, v157, v148
	s_waitcnt lgkmcnt(1)
	v_mfma_f32_32x32x16_bf16 v[82:97], v[100:103], v[128:131], v[82:97]
	v_add_f32_e32 v148, v140, v148
	v_add_f32_e32 v148, v141, v148
	v_add_f32_e32 v148, v142, v148
	s_waitcnt lgkmcnt(0)
	v_mfma_f32_32x32x16_bf16 v[66:81], v[136:139], v[128:131], v[66:81]
	v_add_f32_e32 v148, v143, v148
	v_add_f32_e32 v148, v144, v148
	v_add_f32_e32 v148, v145, v148
	ds_read_b128 v[100:103], v194 offset:49152
	ds_read_b128 v[136:139], v194 offset:57344
	s_waitcnt lgkmcnt(1)
	v_mfma_f32_32x32x16_bf16 v[82:97], v[100:103], v[124:127], v[82:97]
	v_add_f32_e32 v148, v146, v148
	v_add_f32_e32 v199, v147, v148
	v_mov_b32_e32 v200, v199
	s_nop 1
	v_permlane32_swap_b32_e32 v199, v200
	s_waitcnt lgkmcnt(0)
	v_mfma_f32_32x32x16_bf16 v[66:81], v[136:139], v[124:127], v[66:81]
	v_cvt_pk_bf16_f32 v148, v231, v233
	v_cvt_pk_bf16_f32 v149, v229, v232
	v_cvt_pk_bf16_f32 v150, v228, v230
	ds_read_b128 v[100:103], v195 offset:49152
	ds_read_b128 v[136:139], v195 offset:57344
	s_waitcnt lgkmcnt(1)
	v_mfma_f32_32x32x16_bf16 v[82:97], v[100:103], v[120:123], v[82:97]
	v_cvt_pk_bf16_f32 v151, v226, v227
	v_cvt_pk_bf16_f32 v152, v223, v225
	v_cvt_pk_bf16_f32 v153, v209, v224
	s_waitcnt lgkmcnt(0)
	v_mfma_f32_32x32x16_bf16 v[66:81], v[136:139], v[120:123], v[66:81]
	v_cvt_pk_bf16_f32 v154, v206, v208
	v_cvt_pk_bf16_f32 v155, v205, v207
	v_cvt_pk_bf16_f32 v158, v158, v159
	ds_read_b128 v[100:103], v169 offset:49280
	ds_read_b128 v[136:139], v169 offset:57472
	s_waitcnt lgkmcnt(1)
	v_mfma_f32_32x32x16_bf16 v[82:97], v[100:103], v[116:119], v[82:97]
	v_cvt_pk_bf16_f32 v159, v156, v157
	v_cvt_pk_bf16_f32 v156, v178, v179
	v_cvt_pk_bf16_f32 v157, v162, v163
	s_waitcnt lgkmcnt(0)
	v_mfma_f32_32x32x16_bf16 v[66:81], v[136:139], v[116:119], v[66:81]
	v_cvt_pk_bf16_f32 v160, v140, v141
	v_cvt_pk_bf16_f32 v161, v142, v143
	ds_read_b128 v[100:103], v193 offset:49280
	ds_read_b128 v[136:139], v193 offset:57472
	s_waitcnt lgkmcnt(1)
	v_mfma_f32_32x32x16_bf16 v[82:97], v[100:103], v[112:115], v[82:97]
	v_cvt_pk_bf16_f32 v162, v144, v145
	v_cvt_pk_bf16_f32 v163, v146, v147
	s_waitcnt lgkmcnt(0)
	v_mfma_f32_32x32x16_bf16 v[66:81], v[136:139], v[112:115], v[66:81]
	s_nop 0
	v_permlane32_swap_b32_e32 v148, v150
	v_permlane32_swap_b32_e32 v149, v151
	ds_read_b128 v[100:103], v194 offset:49280
	ds_read_b128 v[136:139], v194 offset:57472
	s_waitcnt lgkmcnt(1)
	v_mfma_f32_32x32x16_bf16 v[82:97], v[100:103], v[108:111], v[82:97]
	v_permlane32_swap_b32_e32 v152, v154
	v_permlane32_swap_b32_e32 v153, v155
	s_waitcnt lgkmcnt(0)
	v_mfma_f32_32x32x16_bf16 v[66:81], v[136:139], v[108:111], v[66:81]
	v_permlane32_swap_b32_e32 v156, v158
	v_permlane32_swap_b32_e32 v157, v159
	ds_read_b128 v[100:103], v195 offset:49280
	ds_read_b128 v[136:139], v195 offset:57472
	ds_read_b64_tr_b16 v[172:173], v185 offset:0
	ds_read_b64_tr_b16 v[174:175], v185 offset:0x800
	ds_read_b64_tr_b16 v[202:203], v185 offset:0x1000
	ds_read_b64_tr_b16 v[204:205], v185 offset:0x1800
	ds_read_b64_tr_b16 v[206:207], v185 offset:0x2000
	ds_read_b64_tr_b16 v[208:209], v185 offset:0x2800
	ds_read_b64_tr_b16 v[224:225], v185 offset:0x3000
	ds_read_b64_tr_b16 v[226:227], v185 offset:0x3800
	s_waitcnt lgkmcnt(9)
	v_mfma_f32_32x32x16_bf16 v[82:97], v[100:103], v[104:107], v[82:97]
	v_permlane32_swap_b32_e32 v160, v162
	v_permlane32_swap_b32_e32 v161, v163
	s_waitcnt lgkmcnt(8)
	v_mfma_f32_32x32x16_bf16 v[66:81], v[136:139], v[104:107], v[66:81]
	v_add_u32_e32 v178, s7, v166
	v_add_u32_e32 v100, 1, v178
	v_add_u32_e32 v102, 33, v178
	v_ashrrev_i32_e32 v101, 31, v100
	v_ashrrev_i32_e32 v103, 31, v102
	v_lshlrev_b64 v[140:141], 8, v[100:101]
	v_lshlrev_b64 v[142:143], 8, v[102:103]
	v_lshl_add_u64 v[100:101], v[238:239], 0, v[140:141]
	v_lshl_add_u64 v[140:141], v[234:235], 0, v[140:141]
	v_lshl_add_u64 v[144:145], v[234:235], 0, v[142:143]
	s_nop 0
	s_nop 0
	s_mov_b32 m0, s32
	s_nop 0
	global_load_lds_dwordx4 v[140:141], off
	s_nop 0
	s_add_i32 m0, s32, 0x2000
	s_nop 0
	global_load_lds_dwordx4 v[144:145], off
	s_waitcnt lgkmcnt(0)
; __device__ __forceinline__ void mask_tile(f32x16& p0, f32x16& p1, int dq, unsigned W) {
;     const float NEG = -__builtin_inff();
; #pragma unroll
;     for (int r = 0; r < 16; ++r) {
;         const int c = (r & 3) + 8 * (r >> 2);
;         if ((unsigned)(dq - c) >= W) p0[r] = NEG;
;         if ((unsigned)(dq - c - 32) >= W) p1[r] = NEG;
;     }
; }
; template <int VB>
; __device__ __forceinline__ void pv_tile(f32x16* o, int vb0, bf16x8 pa0, bf16x8 pa1, bf16x8 pa2, bf16x8 pa3) {
;     ...
;     PV_D0(0); PV_D0(1); PV_D0(2); PV_D0(3);
	s_nop 0
	v_mfma_f32_32x32x16_bf16 v[50:65], v[148:151], v[172:175], v[50:65]
	ds_read_b64_tr_b16 v[172:173], v185 offset:0x200
	ds_read_b64_tr_b16 v[174:175], v185 offset:0xa00
	v_mfma_f32_32x32x16_bf16 v[50:65], v[152:155], v[202:205], v[50:65]
	ds_read_b64_tr_b16 v[202:203], v185 offset:0x1200
	ds_read_b64_tr_b16 v[204:205], v185 offset:0x1a00
	v_mfma_f32_32x32x16_bf16 v[50:65], v[156:159], v[206:209], v[50:65]
	ds_read_b64_tr_b16 v[206:207], v185 offset:0x2200
	ds_read_b64_tr_b16 v[208:209], v185 offset:0x2a00
	v_mfma_f32_32x32x16_bf16 v[50:65], v[160:163], v[224:227], v[50:65]
	ds_read_b64_tr_b16 v[224:225], v185 offset:0x3200
	ds_read_b64_tr_b16 v[226:227], v185 offset:0x3a00
	s_waitcnt lgkmcnt(0)
	v_mfma_f32_32x32x16_bf16 v[34:49], v[148:151], v[172:175], v[34:49]
	ds_read_b64_tr_b16 v[172:173], v185 offset:0x400
	ds_read_b64_tr_b16 v[174:175], v185 offset:0xc00
	v_mfma_f32_32x32x16_bf16 v[34:49], v[152:155], v[202:205], v[34:49]
	ds_read_b64_tr_b16 v[202:203], v185 offset:0x1400
	ds_read_b64_tr_b16 v[204:205], v185 offset:0x1c00
	v_mfma_f32_32x32x16_bf16 v[34:49], v[156:159], v[206:209], v[34:49]
	ds_read_b64_tr_b16 v[206:207], v185 offset:0x2400
	ds_read_b64_tr_b16 v[208:209], v185 offset:0x2c00
	v_mfma_f32_32x32x16_bf16 v[34:49], v[160:163], v[224:227], v[34:49]
	ds_read_b64_tr_b16 v[224:225], v185 offset:0x3400
	ds_read_b64_tr_b16 v[226:227], v185 offset:0x3c00
	s_waitcnt lgkmcnt(0)
	v_mfma_f32_32x32x16_bf16 v[18:33], v[148:151], v[172:175], v[18:33]
	ds_read_b64_tr_b16 v[172:173], v185 offset:0x600
	ds_read_b64_tr_b16 v[174:175], v185 offset:0xe00
	v_mfma_f32_32x32x16_bf16 v[18:33], v[152:155], v[202:205], v[18:33]
	ds_read_b64_tr_b16 v[202:203], v185 offset:0x1600
	ds_read_b64_tr_b16 v[204:205], v185 offset:0x1e00
	v_mfma_f32_32x32x16_bf16 v[18:33], v[156:159], v[206:209], v[18:33]
	ds_read_b64_tr_b16 v[206:207], v185 offset:0x2600
	ds_read_b64_tr_b16 v[208:209], v185 offset:0x2e00
	v_mfma_f32_32x32x16_bf16 v[18:33], v[160:163], v[224:227], v[18:33]
	ds_read_b64_tr_b16 v[224:225], v185 offset:0x3600
	ds_read_b64_tr_b16 v[226:227], v185 offset:0x3e00
	s_waitcnt lgkmcnt(0)
	v_mfma_f32_32x32x16_bf16 v[2:17], v[148:151], v[172:175], v[2:17]
	s_cmp_le_i32 s7, s6
	v_mfma_f32_32x32x16_bf16 v[2:17], v[152:155], v[202:205], v[2:17]
	v_mfma_f32_32x32x16_bf16 v[2:17], v[156:159], v[206:209], v[2:17]
	v_mfma_f32_32x32x16_bf16 v[2:17], v[160:163], v[224:227], v[2:17]
	s_cbranch_scc1 .LBB0_91
	v_add_u32_e32 v148, 0x4000007b, v197
	v_cmp_gt_u32_e32 vcc, 2.0, v148
	v_add_u32_e32 v148, 0x5b, v197
	s_nop 0
	v_cndmask_b32_e32 v82, v220, v82, vcc
	v_cmp_lt_u32_e32 vcc, s33, v148
	v_add_u32_e32 v148, 0x7a, v197
	s_nop 0
	v_cndmask_b32_e32 v66, v220, v66, vcc
	v_cmp_lt_u32_e32 vcc, s33, v148
	v_add_u32_e32 v148, 0x5a, v197
	s_nop 0
	v_cndmask_b32_e32 v83, v220, v83, vcc
	v_cmp_lt_u32_e32 vcc, s33, v148
	v_add_u32_e32 v148, 0x79, v197
	s_nop 0
	v_cndmask_b32_e32 v67, v220, v67, vcc
	v_cmp_lt_u32_e32 vcc, s33, v148
	v_add_u32_e32 v148, 0x59, v197
	s_nop 0
	v_cndmask_b32_e32 v84, v220, v84, vcc
	v_cmp_lt_u32_e32 vcc, s33, v148
	v_add_u32_e32 v148, 0x78, v197
	s_nop 0
	v_cndmask_b32_e32 v68, v220, v68, vcc
	v_cmp_lt_u32_e32 vcc, s33, v148
	v_add_u32_e32 v148, 0x58, v197
	s_nop 0
	v_cndmask_b32_e32 v85, v220, v85, vcc
	v_cmp_lt_u32_e32 vcc, s33, v148
	v_add_u32_e32 v148, 0x73, v197
	s_nop 0
	v_cndmask_b32_e32 v69, v220, v69, vcc
	v_cmp_lt_u32_e32 vcc, s33, v148
	v_add_u32_e32 v148, 0x53, v197
	s_nop 0
	v_cndmask_b32_e32 v86, v220, v86, vcc
	v_cmp_lt_u32_e32 vcc, s33, v148
	v_add_u32_e32 v148, 0x72, v197
	s_nop 0
	v_cndmask_b32_e32 v70, v220, v70, vcc
	v_cmp_lt_u32_e32 vcc, s33, v148
	v_add_u32_e32 v148, 0x52, v197
	s_nop 0
	v_cndmask_b32_e32 v87, v220, v87, vcc
	v_cmp_lt_u32_e32 vcc, s33, v148
	v_add_u32_e32 v148, 0x71, v197
	s_nop 0
	v_cndmask_b32_e32 v71, v220, v71, vcc
	v_cmp_lt_u32_e32 vcc, s33, v148
	v_add_u32_e32 v148, 0x51, v197
	s_nop 0
	v_cndmask_b32_e32 v88, v220, v88, vcc
	v_cmp_lt_u32_e32 vcc, s33, v148
	v_add_u32_e32 v148, 0x70, v197
	s_nop 0
	v_cndmask_b32_e32 v72, v220, v72, vcc
	v_cmp_lt_u32_e32 vcc, s33, v148
	v_add_u32_e32 v148, 0x50, v197
	s_nop 0
	v_cndmask_b32_e32 v89, v220, v89, vcc
	v_cmp_lt_u32_e32 vcc, s33, v148
	v_add_u32_e32 v148, 0x6b, v197
	s_nop 0
	v_cndmask_b32_e32 v73, v220, v73, vcc
	v_cmp_lt_u32_e32 vcc, s33, v148
	v_add_u32_e32 v148, 0x4b, v197
	s_nop 0
	v_cndmask_b32_e32 v90, v220, v90, vcc
	v_cmp_lt_u32_e32 vcc, s33, v148
	v_add_u32_e32 v148, 0x6a, v197
	s_nop 0
	v_cndmask_b32_e32 v74, v220, v74, vcc
	v_cmp_lt_u32_e32 vcc, s33, v148
	v_add_u32_e32 v148, 0x4a, v197
	s_nop 0
	v_cndmask_b32_e32 v91, v220, v91, vcc
	v_cmp_lt_u32_e32 vcc, s33, v148
	v_add_u32_e32 v148, 0x69, v197
	s_nop 0
	v_cndmask_b32_e32 v75, v220, v75, vcc
	v_cmp_lt_u32_e32 vcc, s33, v148
	v_add_u32_e32 v148, 0x49, v197
	s_nop 0
	v_cndmask_b32_e32 v92, v220, v92, vcc
	v_cmp_lt_u32_e32 vcc, s33, v148
	v_add_u32_e32 v148, 0x68, v197
	s_nop 0
	v_cndmask_b32_e32 v76, v220, v76, vcc
	v_cmp_lt_u32_e32 vcc, s33, v148
	v_add_u32_e32 v148, 0x48, v197
	s_nop 0
	v_cndmask_b32_e32 v93, v220, v93, vcc
	v_cmp_lt_u32_e32 vcc, s33, v148
	v_add_u32_e32 v148, 0x63, v197
	s_nop 0
	v_cndmask_b32_e32 v77, v220, v77, vcc
	v_cmp_lt_u32_e32 vcc, s33, v148
	v_add_u32_e32 v148, 0x43, v197
	s_nop 0
	v_cndmask_b32_e32 v94, v220, v94, vcc
	v_cmp_lt_u32_e32 vcc, s33, v148
	v_add_u32_e32 v148, 0x62, v197
	s_nop 0
	v_cndmask_b32_e32 v78, v220, v78, vcc
	v_cmp_lt_u32_e32 vcc, s33, v148
	v_add_u32_e32 v148, 0x42, v197
	s_nop 0
	v_cndmask_b32_e32 v95, v220, v95, vcc
	v_cmp_lt_u32_e32 vcc, s33, v148
	v_add_u32_e32 v148, 0x61, v197
	s_nop 0
	v_cndmask_b32_e32 v79, v220, v79, vcc
	v_cmp_lt_u32_e32 vcc, s33, v148
	v_add_u32_e32 v148, 0x41, v197
	s_nop 0
	v_cndmask_b32_e32 v96, v220, v96, vcc
	v_cmp_lt_u32_e32 vcc, s33, v148
	v_add_u32_e32 v148, 0x60, v197
	s_nop 0
	v_cndmask_b32_e32 v80, v220, v80, vcc
	v_cmp_lt_u32_e32 vcc, s33, v148
	v_add_u32_e32 v148, 64, v197
	s_nop 0
	v_cndmask_b32_e32 v97, v220, v97, vcc
	v_cmp_lt_u32_e32 vcc, s33, v148
	s_nop 1
	v_cndmask_b32_e32 v81, v220, v81, vcc

; __device__ __forceinline__ void partialSM(f32x16& p0, f32x16& p1, float& m_reg, float& mn, float& alpha, bool rs) {
;     ...
;     if (__builtin_expect(__all((pmax - m_reg) * SCALE <= THR), 1)) { mn = m_reg; alpha = 1.f; }
;     else { mn = fmaxf(m_reg, pmax); alpha = __builtin_amdgcn_exp2f((m_reg - mn) * C2); m_reg = mn; }
;     const float mnL = rs ? -mn * C2 : -__builtin_inff();
;     for (int r = 0; r < 16; ++r) p0[r] = fmaf(p0[r], C2, mnL); for (int r = 0; r < 16; ++r) p1[r] = fmaf(p1[r], C2, mnL);
;     for (int r = 0; r < 16; ++r) p0[r] = __builtin_amdgcn_exp2f(p0[r]);
; }
.LBB0_95:
	v_cndmask_b32_e64 v179, v148, v198, s[42:43]
	v_mul_f32_e32 v148, 0xbe0293ee, v179
	v_cndmask_b32_e64 v180, v220, v148, s[40:41]
	v_fmamk_f32 v82, v82, 0x3e0293ee, v180
	v_fmamk_f32 v83, v83, 0x3e0293ee, v180
	v_fmamk_f32 v84, v84, 0x3e0293ee, v180
	v_fmamk_f32 v85, v85, 0x3e0293ee, v180
	v_fmamk_f32 v86, v86, 0x3e0293ee, v180
	v_fmamk_f32 v87, v87, 0x3e0293ee, v180
	v_fmamk_f32 v88, v88, 0x3e0293ee, v180
	v_fmamk_f32 v89, v89, 0x3e0293ee, v180
	v_fmamk_f32 v90, v90, 0x3e0293ee, v180
	v_fmamk_f32 v91, v91, 0x3e0293ee, v180
	v_fmamk_f32 v92, v92, 0x3e0293ee, v180
	v_fmamk_f32 v93, v93, 0x3e0293ee, v180
	v_fmamk_f32 v94, v94, 0x3e0293ee, v180
	v_fmamk_f32 v95, v95, 0x3e0293ee, v180
	v_fmamk_f32 v96, v96, 0x3e0293ee, v180
	v_fmamk_f32 v97, v97, 0x3e0293ee, v180
	v_exp_f32_e32 v148, v82
	v_exp_f32_e32 v163, v83
	v_exp_f32_e32 v149, v84
	v_exp_f32_e32 v162, v85
	v_exp_f32_e32 v150, v86
	v_exp_f32_e32 v161, v87
	v_exp_f32_e32 v151, v88
	v_exp_f32_e32 v160, v89
	v_exp_f32_e32 v152, v90
	v_exp_f32_e32 v159, v91
	v_exp_f32_e32 v153, v92
	v_exp_f32_e32 v158, v93
	v_exp_f32_e32 v154, v94
	v_exp_f32_e32 v157, v95
	v_exp_f32_e32 v155, v96
	v_exp_f32_e32 v156, v97
	v_fmamk_f32 v203, v73, 0x3e0293ee, v180
	v_fmamk_f32 v204, v74, 0x3e0293ee, v180
	v_fmamk_f32 v208, v66, 0x3e0293ee, v180
	v_fmamk_f32 v209, v67, 0x3e0293ee, v180
	v_fmamk_f32 v223, v68, 0x3e0293ee, v180
	v_fmamk_f32 v224, v69, 0x3e0293ee, v180
	v_fmamk_f32 v225, v70, 0x3e0293ee, v180
	v_fmamk_f32 v198, v71, 0x3e0293ee, v180
	v_fmamk_f32 v201, v72, 0x3e0293ee, v180
	v_fmamk_f32 v205, v75, 0x3e0293ee, v180
	v_fmamk_f32 v206, v76, 0x3e0293ee, v180
	v_fmamk_f32 v207, v77, 0x3e0293ee, v180
	v_fmamk_f32 v181, v78, 0x3e0293ee, v180
	v_fmamk_f32 v226, v79, 0x3e0293ee, v180
	v_fmamk_f32 v227, v80, 0x3e0293ee, v180
	v_fmac_f32_e32 v180, 0x3e0293ee, v81
	s_waitcnt lgkmcnt(0)
	s_barrier
; __device__ __forceinline__ void finishSM(f32x16& p0, f32x16& p1, float alpha, float& l_reg, bf16x8& pa0, bf16x8& pa1, bf16x8& pa2, bf16x8& pa3) {
;     for (int r = 0; r < 16; ++r) p1[r] = __builtin_amdgcn_exp2f(p1[r]);
;     float ps = 0; for (int r = 0; r < 16; ++r) ps += p0[r]; for (int r = 0; r < 16; ++r) ps += p1[r];
;     { auto rr = __builtin_amdgcn_permlane32_swap(__float_as_uint(ps), __float_as_uint(ps), false, false);
;       ps = __uint_as_float(rr[0]) + __uint_as_float(rr[1]); }
;     l_reg = l_reg * alpha + ps;
;     ...
;     PK4(p0, 0, pa0); PK4(p0, 8, pa1); PK4(p1, 0, pa2); PK4(p1, 8, pa3);
;     ...
; }
; template <int KB>
; __device__ __forceinline__ void qkt(f32x16& p0, f32x16& p1, const char* K_lds, int r32, int hi, const bf16x8* qr) {
;     p0 = f32x16{}; p1 = f32x16{};
;     const char* kb[4];
; #pragma unroll
;     for (int dd = 0; dd < 4; ++dd) kb[dd] = K_lds + KB * SHM_K + KSWZ(r32, (dd * 16 + hi * 8) * 2);
; #pragma unroll
;     for (int d0 = 0; d0 < 8; ++d0) { const char* a = kb[d0 & 3] + (d0 >> 2) * 128;
;         bf16x8 b0 = *reinterpret_cast<const bf16x8*>(a);
;         bf16x8 b1 = *reinterpret_cast<const bf16x8*>(a + 32 * 256);
;         p0 = __builtin_amdgcn_mfma_f32_32x32x16_bf16(b0, qr[d0], p0, 0, 0, 0);
;         p1 = __builtin_amdgcn_mfma_f32_32x32x16_bf16(b1, qr[d0], p1, 0, 0, 0); }
; }
	ds_read_b128 v[66:69], v169 offset:32768
	ds_read_b128 v[70:73], v169 offset:40960
	ds_read_b128 v[172:175], v193 offset:32768
	ds_read_b128 v[228:231], v193 offset:40960
	s_lshl_b32 m0, s32, 1
	s_sub_i32 m0, m0, 0x10000
	s_nop 0
	global_load_lds_dwordx4 v[100:101], off
	s_add_i32 m0, m0, 896
	s_nop 0
	global_load_lds_dwordx4 v[100:101], off offset:128
	v_exp_f32_e32 v198, v198
	v_exp_f32_e32 v201, v201
	v_exp_f32_e32 v214, v204
	v_exp_f32_e32 v205, v205
	v_exp_f32_e32 v206, v206
	v_exp_f32_e32 v207, v207
	v_exp_f32_e32 v181, v181
	v_exp_f32_e32 v215, v226
	v_exp_f32_e32 v216, v227
	v_exp_f32_e32 v180, v180
	v_exp_f32_e32 v218, v209
	v_exp_f32_e32 v209, v203
	v_add_f32_e32 v203, 0, v148
	v_add_f32_e32 v203, v163, v203
	v_add_f32_e32 v203, v149, v203
	v_add_f32_e32 v203, v162, v203
	v_add_f32_e32 v203, v150, v203
	v_add_f32_e32 v203, v161, v203
	v_add_f32_e32 v203, v151, v203
	v_add_f32_e32 v203, v160, v203
	v_add_f32_e32 v203, v152, v203
	v_add_f32_e32 v203, v159, v203
	v_add_f32_e32 v203, v153, v203
	v_add_f32_e32 v203, v158, v203
	v_exp_f32_e32 v217, v208
	v_add_f32_e32 v203, v154, v203
	v_add_f32_e32 v203, v157, v203
	v_exp_f32_e32 v219, v223
	v_add_f32_e32 v203, v155, v203
	v_exp_f32_e32 v222, v224
	v_add_f32_e32 v203, v156, v203
	v_exp_f32_e32 v208, v225
	v_add_f32_e32 v203, v217, v203
	v_add_f32_e32 v203, v218, v203
	s_waitcnt lgkmcnt(3)
	v_mfma_f32_32x32x16_bf16 v[82:97], v[66:69], v[132:135], 0
	v_add_f32_e32 v203, v219, v203
	v_add_f32_e32 v203, v222, v203
	v_add_f32_e32 v203, v208, v203
	s_waitcnt lgkmcnt(2)
	v_mfma_f32_32x32x16_bf16 v[66:81], v[70:73], v[132:135], 0
	v_add_f32_e32 v203, v198, v203
	v_add_f32_e32 v203, v201, v203
	v_add_f32_e32 v203, v209, v203
	s_waitcnt lgkmcnt(1)
	v_mfma_f32_32x32x16_bf16 v[82:97], v[172:175], v[128:131], v[82:97]
	v_add_f32_e32 v203, v214, v203
	v_add_f32_e32 v203, v205, v203
	v_add_f32_e32 v203, v206, v203
	s_waitcnt lgkmcnt(0)
	v_mfma_f32_32x32x16_bf16 v[66:81], v[228:231], v[128:131], v[66:81]
	v_add_f32_e32 v203, v207, v203
	v_add_f32_e32 v203, v181, v203
	v_add_f32_e32 v203, v215, v203
	ds_read_b128 v[172:175], v194 offset:32768
	ds_read_b128 v[228:231], v194 offset:40960
	s_waitcnt lgkmcnt(1)
	v_mfma_f32_32x32x16_bf16 v[82:97], v[172:175], v[124:127], v[82:97]
	v_add_f32_e32 v203, v216, v203
	v_add_f32_e32 v203, v180, v203
	v_mov_b32_e32 v204, v203
	s_waitcnt lgkmcnt(0)
	v_mfma_f32_32x32x16_bf16 v[66:81], v[228:231], v[124:127], v[66:81]
	v_cvt_pk_bf16_f32 v148, v148, v163
	v_cvt_pk_bf16_f32 v149, v149, v162
	v_cvt_pk_bf16_f32 v150, v150, v161
	ds_read_b128 v[172:175], v195 offset:32768
	ds_read_b128 v[228:231], v195 offset:40960
	s_waitcnt lgkmcnt(1)
	v_mfma_f32_32x32x16_bf16 v[82:97], v[172:175], v[120:123], v[82:97]
	v_cvt_pk_bf16_f32 v151, v151, v160
	v_cvt_pk_bf16_f32 v152, v152, v159
	v_cvt_pk_bf16_f32 v153, v153, v158
	s_waitcnt lgkmcnt(0)
	v_mfma_f32_32x32x16_bf16 v[66:81], v[228:231], v[120:123], v[66:81]
	v_cvt_pk_bf16_f32 v154, v154, v157
	v_cvt_pk_bf16_f32 v155, v155, v156
	v_cvt_pk_bf16_f32 v156, v217, v218
	ds_read_b128 v[172:175], v169 offset:32896
	ds_read_b128 v[228:231], v169 offset:41088
	s_waitcnt lgkmcnt(1)
	v_mfma_f32_32x32x16_bf16 v[82:97], v[172:175], v[116:119], v[82:97]
	v_cvt_pk_bf16_f32 v157, v219, v222
	v_cvt_pk_bf16_f32 v158, v208, v198
	v_cvt_pk_bf16_f32 v159, v201, v209
	s_waitcnt lgkmcnt(0)
	v_mfma_f32_32x32x16_bf16 v[66:81], v[228:231], v[116:119], v[66:81]
	v_cvt_pk_bf16_f32 v160, v214, v205
	v_cvt_pk_bf16_f32 v161, v206, v207
	v_cvt_pk_bf16_f32 v162, v181, v215
	ds_read_b128 v[172:175], v193 offset:32896
	ds_read_b128 v[228:231], v193 offset:41088
	s_waitcnt lgkmcnt(1)
	v_mfma_f32_32x32x16_bf16 v[82:97], v[172:175], v[112:115], v[82:97]
	v_cvt_pk_bf16_f32 v163, v216, v180
	s_nop 1
	v_permlane32_swap_b32_e32 v203, v204
	s_waitcnt lgkmcnt(0)
	v_mfma_f32_32x32x16_bf16 v[66:81], v[228:231], v[112:115], v[66:81]
	v_permlane32_swap_b32_e32 v148, v150
	v_permlane32_swap_b32_e32 v149, v151
	ds_read_b128 v[172:175], v194 offset:32896
	ds_read_b128 v[228:231], v194 offset:41088
	s_waitcnt lgkmcnt(1)
	v_mfma_f32_32x32x16_bf16 v[82:97], v[172:175], v[108:111], v[82:97]
	v_permlane32_swap_b32_e32 v152, v154
	v_permlane32_swap_b32_e32 v153, v155
	s_waitcnt lgkmcnt(0)
	v_mfma_f32_32x32x16_bf16 v[66:81], v[228:231], v[108:111], v[66:81]
	v_permlane32_swap_b32_e32 v156, v158
	v_permlane32_swap_b32_e32 v157, v159
	ds_read_b128 v[172:175], v195 offset:32896
	ds_read_b128 v[228:231], v195 offset:41088
	ds_read_b64_tr_b16 v[206:207], v185 offset:0x5000
	ds_read_b64_tr_b16 v[208:209], v185 offset:0x5800
	ds_read_b64_tr_b16 v[224:225], v185 offset:0x6000
	ds_read_b64_tr_b16 v[226:227], v185 offset:0x6800
	s_waitcnt lgkmcnt(5)
	v_mfma_f32_32x32x16_bf16 v[82:97], v[172:175], v[104:107], v[82:97]
	v_permlane32_swap_b32_e32 v160, v162
	v_permlane32_swap_b32_e32 v161, v163
	s_waitcnt lgkmcnt(4)
	v_mfma_f32_32x32x16_bf16 v[66:81], v[228:231], v[104:107], v[66:81]
	ds_read_b64_tr_b16 v[172:173], v185 offset:0x4000
	ds_read_b64_tr_b16 v[174:175], v185 offset:0x4800
	ds_read_b64_tr_b16 v[228:229], v185 offset:0x7000
	ds_read_b64_tr_b16 v[230:231], v185 offset:0x7800
	s_cmp_lt_u32 s3, s2
	s_cselect_b64 s[22:23], -1, 0
	s_cmp_ge_u32 s3, s2
	s_cbranch_scc1 .LBB0_97
	v_add_u32_e32 v242, 0x41, v178
	v_add_u32_e32 v246, 0x61, v178
	v_ashrrev_i32_e32 v243, 31, v242
	v_ashrrev_i32_e32 v247, 31, v246
	v_lshlrev_b64 v[140:141], 8, v[242:243]
	v_lshlrev_b64 v[142:143], 8, v[246:247]
	v_lshl_add_u64 v[242:243], v[238:239], 0, v[140:141]
	v_lshl_add_u64 v[140:141], v[234:235], 0, v[140:141]
	v_lshl_add_u64 v[144:145], v[234:235], 0, v[142:143]
	s_nop 0
	s_nop 0
	s_add_i32 m0, s32, 0x4000
	s_nop 0
	global_load_lds_dwordx4 v[140:141], off
	s_nop 0
	s_add_i32 m0, s32, 0x6000
	s_nop 0
	global_load_lds_dwordx4 v[144:145], off
	s_mov_b32 s100, 1
